# hand-written SwiGLU epilogue on natural accumulator pairs (no shuffle moves, 32-bit store offsets), same f32 op order
# speedup vs baseline: 1.1282x; 1.0035x over previous
.LBB0_1006:
	v_lshl_add_u32 v144, s0, 8, v148
	v_ashrrev_i32_e32 v145, 31, v144
	v_lshl_add_u64 v[146:147], v[144:145], 2, s[8:9]
	global_load_dword v170, v[146:147], off
	global_load_dword v171, v[146:147], off offset:64
	global_load_dword v172, v[146:147], off offset:128
	global_load_dword v173, v[146:147], off offset:192
	global_load_dword v174, v[146:147], off offset:512
	global_load_dword v175, v[146:147], off offset:576
	global_load_dword v176, v[146:147], off offset:640
	global_load_dword v177, v[146:147], off offset:704
	v_lshl_add_u32 v156, s1, 7, v150
	v_readlane_b32 s0, v255, 0
	v_readlane_b32 s1, v255, 1
	v_mul_lo_u32 v161, v144, s41
	v_mov_b32_e32 v158, 0xbfb8aa3b
	v_mov_b32_e32 v160, 1.0
	v_lshl_add_u32 v161, v156, 1, v161
	s_waitcnt vmcnt(0)
	v_fmamk_f32 v144, v170, 0x3a800000, v154
	v_mul_f32_e32 v145, 0x4b800000, v144
	v_cmp_gt_f32_e32 vcc, s40, v144
	s_nop 1
	v_cndmask_b32_e32 v144, v144, v145, vcc
	v_rsq_f32_e32 v144, v144
	s_nop 0
	v_mul_f32_e32 v145, 0x45800000, v144
	v_cndmask_b32_e32 v146, v144, v145, vcc
	v_pk_mul_f32 v[116:117], v[116:117], v[146:147] op_sel_hi:[1,0]
	v_pk_mul_f32 v[118:119], v[118:119], v[146:147] op_sel_hi:[1,0]
	v_pk_mul_f32 v[112:113], v[112:113], v[146:147] op_sel_hi:[1,0]
	v_pk_mul_f32 v[114:115], v[114:115], v[146:147] op_sel_hi:[1,0]
	v_pk_mul_f32 v[124:125], v[124:125], v[146:147] op_sel_hi:[1,0]
	v_pk_mul_f32 v[126:127], v[126:127], v[146:147] op_sel_hi:[1,0]
	v_pk_mul_f32 v[120:121], v[120:121], v[146:147] op_sel_hi:[1,0]
	v_pk_mul_f32 v[122:123], v[122:123], v[146:147] op_sel_hi:[1,0]
	v_pk_mul_f32 v[162:163], v[116:117], v[158:159] op_sel_hi:[1,0]
	v_pk_mul_f32 v[164:165], v[118:119], v[158:159] op_sel_hi:[1,0]
	v_pk_mul_f32 v[166:167], v[112:113], v[158:159] op_sel_hi:[1,0]
	v_pk_mul_f32 v[168:169], v[114:115], v[158:159] op_sel_hi:[1,0]
	v_exp_f32_e32 v162, v162
	v_exp_f32_e32 v163, v163
	v_exp_f32_e32 v164, v164
	v_exp_f32_e32 v165, v165
	v_exp_f32_e32 v166, v166
	v_exp_f32_e32 v167, v167
	v_exp_f32_e32 v168, v168
	v_exp_f32_e32 v169, v169
	v_pk_add_f32 v[162:163], v[162:163], v[160:161] op_sel_hi:[1,0]
	v_pk_add_f32 v[164:165], v[164:165], v[160:161] op_sel_hi:[1,0]
	v_pk_add_f32 v[166:167], v[166:167], v[160:161] op_sel_hi:[1,0]
	v_pk_add_f32 v[168:169], v[168:169], v[160:161] op_sel_hi:[1,0]
	v_rcp_f32_e32 v162, v162
	v_rcp_f32_e32 v163, v163
	v_rcp_f32_e32 v164, v164
	v_rcp_f32_e32 v165, v165
	v_rcp_f32_e32 v166, v166
	v_rcp_f32_e32 v167, v167
	v_rcp_f32_e32 v168, v168
	v_rcp_f32_e32 v169, v169
	v_pk_mul_f32 v[162:163], v[116:117], v[162:163]
	v_pk_mul_f32 v[164:165], v[118:119], v[164:165]
	v_pk_mul_f32 v[166:167], v[112:113], v[166:167]
	v_pk_mul_f32 v[168:169], v[114:115], v[168:169]
	v_pk_mul_f32 v[162:163], v[124:125], v[162:163]
	v_pk_mul_f32 v[164:165], v[126:127], v[164:165]
	v_pk_mul_f32 v[166:167], v[120:121], v[166:167]
	v_pk_mul_f32 v[168:169], v[122:123], v[168:169]
	v_cvt_pk_bf16_f32 v112, v162, v163
	v_cvt_pk_bf16_f32 v113, v164, v165
	v_cvt_pk_bf16_f32 v114, v166, v167
	v_cvt_pk_bf16_f32 v115, v168, v169
	global_store_dwordx4 v161, v[112:115], s[0:1]
	v_add_u32_e32 v161, 0x16000, v161
	v_fmamk_f32 v144, v171, 0x3a800000, v154
	v_mul_f32_e32 v145, 0x4b800000, v144
	v_cmp_gt_f32_e32 vcc, s40, v144
	s_nop 1
	v_cndmask_b32_e32 v144, v144, v145, vcc
	v_rsq_f32_e32 v144, v144
	s_nop 0
	v_mul_f32_e32 v145, 0x45800000, v144
	v_cndmask_b32_e32 v146, v144, v145, vcc
	v_pk_mul_f32 v[100:101], v[100:101], v[146:147] op_sel_hi:[1,0]
	v_pk_mul_f32 v[102:103], v[102:103], v[146:147] op_sel_hi:[1,0]
	v_pk_mul_f32 v[96:97], v[96:97], v[146:147] op_sel_hi:[1,0]
	v_pk_mul_f32 v[98:99], v[98:99], v[146:147] op_sel_hi:[1,0]
	v_pk_mul_f32 v[108:109], v[108:109], v[146:147] op_sel_hi:[1,0]
	v_pk_mul_f32 v[110:111], v[110:111], v[146:147] op_sel_hi:[1,0]
	v_pk_mul_f32 v[104:105], v[104:105], v[146:147] op_sel_hi:[1,0]
	v_pk_mul_f32 v[106:107], v[106:107], v[146:147] op_sel_hi:[1,0]
	v_pk_mul_f32 v[162:163], v[100:101], v[158:159] op_sel_hi:[1,0]
	v_pk_mul_f32 v[164:165], v[102:103], v[158:159] op_sel_hi:[1,0]
	v_pk_mul_f32 v[166:167], v[96:97], v[158:159] op_sel_hi:[1,0]
	v_pk_mul_f32 v[168:169], v[98:99], v[158:159] op_sel_hi:[1,0]
	v_exp_f32_e32 v162, v162
	v_exp_f32_e32 v163, v163
	v_exp_f32_e32 v164, v164
	v_exp_f32_e32 v165, v165
	v_exp_f32_e32 v166, v166
	v_exp_f32_e32 v167, v167
	v_exp_f32_e32 v168, v168
	v_exp_f32_e32 v169, v169
	v_pk_add_f32 v[162:163], v[162:163], v[160:161] op_sel_hi:[1,0]
	v_pk_add_f32 v[164:165], v[164:165], v[160:161] op_sel_hi:[1,0]
	v_pk_add_f32 v[166:167], v[166:167], v[160:161] op_sel_hi:[1,0]
	v_pk_add_f32 v[168:169], v[168:169], v[160:161] op_sel_hi:[1,0]
	v_rcp_f32_e32 v162, v162
	v_rcp_f32_e32 v163, v163
	v_rcp_f32_e32 v164, v164
	v_rcp_f32_e32 v165, v165
	v_rcp_f32_e32 v166, v166
	v_rcp_f32_e32 v167, v167
	v_rcp_f32_e32 v168, v168
	v_rcp_f32_e32 v169, v169
	v_pk_mul_f32 v[162:163], v[100:101], v[162:163]
	v_pk_mul_f32 v[164:165], v[102:103], v[164:165]
	v_pk_mul_f32 v[166:167], v[96:97], v[166:167]
	v_pk_mul_f32 v[168:169], v[98:99], v[168:169]
	v_pk_mul_f32 v[162:163], v[108:109], v[162:163]
	v_pk_mul_f32 v[164:165], v[110:111], v[164:165]
	v_pk_mul_f32 v[166:167], v[104:105], v[166:167]
	v_pk_mul_f32 v[168:169], v[106:107], v[168:169]
	v_cvt_pk_bf16_f32 v96, v162, v163
	v_cvt_pk_bf16_f32 v97, v164, v165
	v_cvt_pk_bf16_f32 v98, v166, v167
	v_cvt_pk_bf16_f32 v99, v168, v169
	global_store_dwordx4 v161, v[96:99], s[0:1]
	v_add_u32_e32 v161, 0x16000, v161
	v_fmamk_f32 v144, v172, 0x3a800000, v154
	v_mul_f32_e32 v145, 0x4b800000, v144
	v_cmp_gt_f32_e32 vcc, s40, v144
	s_nop 1
	v_cndmask_b32_e32 v144, v144, v145, vcc
	v_rsq_f32_e32 v144, v144
	s_nop 0
	v_mul_f32_e32 v145, 0x45800000, v144
	v_cndmask_b32_e32 v146, v144, v145, vcc
	v_pk_mul_f32 v[84:85], v[84:85], v[146:147] op_sel_hi:[1,0]
	v_pk_mul_f32 v[86:87], v[86:87], v[146:147] op_sel_hi:[1,0]
	v_pk_mul_f32 v[80:81], v[80:81], v[146:147] op_sel_hi:[1,0]
	v_pk_mul_f32 v[82:83], v[82:83], v[146:147] op_sel_hi:[1,0]
	v_pk_mul_f32 v[92:93], v[92:93], v[146:147] op_sel_hi:[1,0]
	v_pk_mul_f32 v[94:95], v[94:95], v[146:147] op_sel_hi:[1,0]
	v_pk_mul_f32 v[88:89], v[88:89], v[146:147] op_sel_hi:[1,0]
	v_pk_mul_f32 v[90:91], v[90:91], v[146:147] op_sel_hi:[1,0]
	v_pk_mul_f32 v[162:163], v[84:85], v[158:159] op_sel_hi:[1,0]
	v_pk_mul_f32 v[164:165], v[86:87], v[158:159] op_sel_hi:[1,0]
	v_pk_mul_f32 v[166:167], v[80:81], v[158:159] op_sel_hi:[1,0]
	v_pk_mul_f32 v[168:169], v[82:83], v[158:159] op_sel_hi:[1,0]
	v_exp_f32_e32 v162, v162
	v_exp_f32_e32 v163, v163
	v_exp_f32_e32 v164, v164
	v_exp_f32_e32 v165, v165
	v_exp_f32_e32 v166, v166
	v_exp_f32_e32 v167, v167
	v_exp_f32_e32 v168, v168
	v_exp_f32_e32 v169, v169
	v_pk_add_f32 v[162:163], v[162:163], v[160:161] op_sel_hi:[1,0]
	v_pk_add_f32 v[164:165], v[164:165], v[160:161] op_sel_hi:[1,0]
	v_pk_add_f32 v[166:167], v[166:167], v[160:161] op_sel_hi:[1,0]
	v_pk_add_f32 v[168:169], v[168:169], v[160:161] op_sel_hi:[1,0]
	v_rcp_f32_e32 v162, v162
	v_rcp_f32_e32 v163, v163
	v_rcp_f32_e32 v164, v164
	v_rcp_f32_e32 v165, v165
	v_rcp_f32_e32 v166, v166
	v_rcp_f32_e32 v167, v167
	v_rcp_f32_e32 v168, v168
	v_rcp_f32_e32 v169, v169
	v_pk_mul_f32 v[162:163], v[84:85], v[162:163]
	v_pk_mul_f32 v[164:165], v[86:87], v[164:165]
	v_pk_mul_f32 v[166:167], v[80:81], v[166:167]
	v_pk_mul_f32 v[168:169], v[82:83], v[168:169]
	v_pk_mul_f32 v[162:163], v[92:93], v[162:163]
	v_pk_mul_f32 v[164:165], v[94:95], v[164:165]
	v_pk_mul_f32 v[166:167], v[88:89], v[166:167]
	v_pk_mul_f32 v[168:169], v[90:91], v[168:169]
	v_cvt_pk_bf16_f32 v80, v162, v163
	v_cvt_pk_bf16_f32 v81, v164, v165
	v_cvt_pk_bf16_f32 v82, v166, v167
	v_cvt_pk_bf16_f32 v83, v168, v169
	global_store_dwordx4 v161, v[80:83], s[0:1]
	v_add_u32_e32 v161, 0x16000, v161
	v_fmamk_f32 v144, v173, 0x3a800000, v154
	v_mul_f32_e32 v145, 0x4b800000, v144
	v_cmp_gt_f32_e32 vcc, s40, v144
	s_nop 1
	v_cndmask_b32_e32 v144, v144, v145, vcc
	v_rsq_f32_e32 v144, v144
	s_nop 0
	v_mul_f32_e32 v145, 0x45800000, v144
	v_cndmask_b32_e32 v146, v144, v145, vcc
	v_pk_mul_f32 v[72:73], v[72:73], v[146:147] op_sel_hi:[1,0]
	v_pk_mul_f32 v[74:75], v[74:75], v[146:147] op_sel_hi:[1,0]
	v_pk_mul_f32 v[64:65], v[64:65], v[146:147] op_sel_hi:[1,0]
	v_pk_mul_f32 v[66:67], v[66:67], v[146:147] op_sel_hi:[1,0]
	v_pk_mul_f32 v[76:77], v[76:77], v[146:147] op_sel_hi:[1,0]
	v_pk_mul_f32 v[78:79], v[78:79], v[146:147] op_sel_hi:[1,0]
	v_pk_mul_f32 v[68:69], v[68:69], v[146:147] op_sel_hi:[1,0]
	v_pk_mul_f32 v[70:71], v[70:71], v[146:147] op_sel_hi:[1,0]
	v_pk_mul_f32 v[162:163], v[72:73], v[158:159] op_sel_hi:[1,0]
	v_pk_mul_f32 v[164:165], v[74:75], v[158:159] op_sel_hi:[1,0]
	v_pk_mul_f32 v[166:167], v[64:65], v[158:159] op_sel_hi:[1,0]
	v_pk_mul_f32 v[168:169], v[66:67], v[158:159] op_sel_hi:[1,0]
	v_exp_f32_e32 v162, v162
	v_exp_f32_e32 v163, v163
	v_exp_f32_e32 v164, v164
	v_exp_f32_e32 v165, v165
	v_exp_f32_e32 v166, v166
	v_exp_f32_e32 v167, v167
	v_exp_f32_e32 v168, v168
	v_exp_f32_e32 v169, v169
	v_pk_add_f32 v[162:163], v[162:163], v[160:161] op_sel_hi:[1,0]
	v_pk_add_f32 v[164:165], v[164:165], v[160:161] op_sel_hi:[1,0]
	v_pk_add_f32 v[166:167], v[166:167], v[160:161] op_sel_hi:[1,0]
	v_pk_add_f32 v[168:169], v[168:169], v[160:161] op_sel_hi:[1,0]
	v_rcp_f32_e32 v162, v162
	v_rcp_f32_e32 v163, v163
	v_rcp_f32_e32 v164, v164
	v_rcp_f32_e32 v165, v165
	v_rcp_f32_e32 v166, v166
	v_rcp_f32_e32 v167, v167
	v_rcp_f32_e32 v168, v168
	v_rcp_f32_e32 v169, v169
	v_pk_mul_f32 v[162:163], v[72:73], v[162:163]
	v_pk_mul_f32 v[164:165], v[74:75], v[164:165]
	v_pk_mul_f32 v[166:167], v[64:65], v[166:167]
	v_pk_mul_f32 v[168:169], v[66:67], v[168:169]
	v_pk_mul_f32 v[162:163], v[76:77], v[162:163]
	v_pk_mul_f32 v[164:165], v[78:79], v[164:165]
	v_pk_mul_f32 v[166:167], v[68:69], v[166:167]
	v_pk_mul_f32 v[168:169], v[70:71], v[168:169]
	v_cvt_pk_bf16_f32 v64, v162, v163
	v_cvt_pk_bf16_f32 v65, v164, v165
	v_cvt_pk_bf16_f32 v66, v166, v167
	v_cvt_pk_bf16_f32 v67, v168, v169
	global_store_dwordx4 v161, v[64:67], s[0:1]
	v_add_u32_e32 v161, 0x6e000, v161
	v_fmamk_f32 v144, v174, 0x3a800000, v154
	v_mul_f32_e32 v145, 0x4b800000, v144
	v_cmp_gt_f32_e32 vcc, s40, v144
	s_nop 1
	v_cndmask_b32_e32 v144, v144, v145, vcc
	v_rsq_f32_e32 v144, v144
	s_nop 0
	v_mul_f32_e32 v145, 0x45800000, v144
	v_cndmask_b32_e32 v146, v144, v145, vcc
	v_pk_mul_f32 v[56:57], v[56:57], v[146:147] op_sel_hi:[1,0]
	v_pk_mul_f32 v[58:59], v[58:59], v[146:147] op_sel_hi:[1,0]
	v_pk_mul_f32 v[48:49], v[48:49], v[146:147] op_sel_hi:[1,0]
	v_pk_mul_f32 v[50:51], v[50:51], v[146:147] op_sel_hi:[1,0]
	v_pk_mul_f32 v[60:61], v[60:61], v[146:147] op_sel_hi:[1,0]
	v_pk_mul_f32 v[62:63], v[62:63], v[146:147] op_sel_hi:[1,0]
	v_pk_mul_f32 v[52:53], v[52:53], v[146:147] op_sel_hi:[1,0]
	v_pk_mul_f32 v[54:55], v[54:55], v[146:147] op_sel_hi:[1,0]
	v_pk_mul_f32 v[162:163], v[56:57], v[158:159] op_sel_hi:[1,0]
	v_pk_mul_f32 v[164:165], v[58:59], v[158:159] op_sel_hi:[1,0]
	v_pk_mul_f32 v[166:167], v[48:49], v[158:159] op_sel_hi:[1,0]
	v_pk_mul_f32 v[168:169], v[50:51], v[158:159] op_sel_hi:[1,0]
	v_exp_f32_e32 v162, v162
	v_exp_f32_e32 v163, v163
	v_exp_f32_e32 v164, v164
	v_exp_f32_e32 v165, v165
	v_exp_f32_e32 v166, v166
	v_exp_f32_e32 v167, v167
	v_exp_f32_e32 v168, v168
	v_exp_f32_e32 v169, v169
	v_pk_add_f32 v[162:163], v[162:163], v[160:161] op_sel_hi:[1,0]
	v_pk_add_f32 v[164:165], v[164:165], v[160:161] op_sel_hi:[1,0]
	v_pk_add_f32 v[166:167], v[166:167], v[160:161] op_sel_hi:[1,0]
	v_pk_add_f32 v[168:169], v[168:169], v[160:161] op_sel_hi:[1,0]
	v_rcp_f32_e32 v162, v162
	v_rcp_f32_e32 v163, v163
	v_rcp_f32_e32 v164, v164
	v_rcp_f32_e32 v165, v165
	v_rcp_f32_e32 v166, v166
	v_rcp_f32_e32 v167, v167
	v_rcp_f32_e32 v168, v168
	v_rcp_f32_e32 v169, v169
	v_pk_mul_f32 v[162:163], v[56:57], v[162:163]
	v_pk_mul_f32 v[164:165], v[58:59], v[164:165]
	v_pk_mul_f32 v[166:167], v[48:49], v[166:167]
	v_pk_mul_f32 v[168:169], v[50:51], v[168:169]
	v_pk_mul_f32 v[162:163], v[60:61], v[162:163]
	v_pk_mul_f32 v[164:165], v[62:63], v[164:165]
	v_pk_mul_f32 v[166:167], v[52:53], v[166:167]
	v_pk_mul_f32 v[168:169], v[54:55], v[168:169]
	v_cvt_pk_bf16_f32 v48, v162, v163
	v_cvt_pk_bf16_f32 v49, v164, v165
	v_cvt_pk_bf16_f32 v50, v166, v167
	v_cvt_pk_bf16_f32 v51, v168, v169
	global_store_dwordx4 v161, v[48:51], s[0:1]
	v_add_u32_e32 v161, 0x16000, v161
	v_fmamk_f32 v144, v175, 0x3a800000, v154
	v_mul_f32_e32 v145, 0x4b800000, v144
	v_cmp_gt_f32_e32 vcc, s40, v144
	s_nop 1
	v_cndmask_b32_e32 v144, v144, v145, vcc
	v_rsq_f32_e32 v144, v144
	s_nop 0
	v_mul_f32_e32 v145, 0x45800000, v144
	v_cndmask_b32_e32 v146, v144, v145, vcc
	v_pk_mul_f32 v[40:41], v[40:41], v[146:147] op_sel_hi:[1,0]
	v_pk_mul_f32 v[42:43], v[42:43], v[146:147] op_sel_hi:[1,0]
	v_pk_mul_f32 v[32:33], v[32:33], v[146:147] op_sel_hi:[1,0]
	v_pk_mul_f32 v[34:35], v[34:35], v[146:147] op_sel_hi:[1,0]
	v_pk_mul_f32 v[44:45], v[44:45], v[146:147] op_sel_hi:[1,0]
	v_pk_mul_f32 v[46:47], v[46:47], v[146:147] op_sel_hi:[1,0]
	v_pk_mul_f32 v[36:37], v[36:37], v[146:147] op_sel_hi:[1,0]
	v_pk_mul_f32 v[38:39], v[38:39], v[146:147] op_sel_hi:[1,0]
	v_pk_mul_f32 v[162:163], v[40:41], v[158:159] op_sel_hi:[1,0]
	v_pk_mul_f32 v[164:165], v[42:43], v[158:159] op_sel_hi:[1,0]
	v_pk_mul_f32 v[166:167], v[32:33], v[158:159] op_sel_hi:[1,0]
	v_pk_mul_f32 v[168:169], v[34:35], v[158:159] op_sel_hi:[1,0]
	v_exp_f32_e32 v162, v162
	v_exp_f32_e32 v163, v163
	v_exp_f32_e32 v164, v164
	v_exp_f32_e32 v165, v165
	v_exp_f32_e32 v166, v166
	v_exp_f32_e32 v167, v167
	v_exp_f32_e32 v168, v168
	v_exp_f32_e32 v169, v169
	v_pk_add_f32 v[162:163], v[162:163], v[160:161] op_sel_hi:[1,0]
	v_pk_add_f32 v[164:165], v[164:165], v[160:161] op_sel_hi:[1,0]
	v_pk_add_f32 v[166:167], v[166:167], v[160:161] op_sel_hi:[1,0]
	v_pk_add_f32 v[168:169], v[168:169], v[160:161] op_sel_hi:[1,0]
	v_rcp_f32_e32 v162, v162
	v_rcp_f32_e32 v163, v163
	v_rcp_f32_e32 v164, v164
	v_rcp_f32_e32 v165, v165
	v_rcp_f32_e32 v166, v166
	v_rcp_f32_e32 v167, v167
	v_rcp_f32_e32 v168, v168
	v_rcp_f32_e32 v169, v169
	v_pk_mul_f32 v[162:163], v[40:41], v[162:163]
	v_pk_mul_f32 v[164:165], v[42:43], v[164:165]
	v_pk_mul_f32 v[166:167], v[32:33], v[166:167]
	v_pk_mul_f32 v[168:169], v[34:35], v[168:169]
	v_pk_mul_f32 v[162:163], v[44:45], v[162:163]
	v_pk_mul_f32 v[164:165], v[46:47], v[164:165]
	v_pk_mul_f32 v[166:167], v[36:37], v[166:167]
	v_pk_mul_f32 v[168:169], v[38:39], v[168:169]
	v_cvt_pk_bf16_f32 v32, v162, v163
	v_cvt_pk_bf16_f32 v33, v164, v165
	v_cvt_pk_bf16_f32 v34, v166, v167
	v_cvt_pk_bf16_f32 v35, v168, v169
	global_store_dwordx4 v161, v[32:35], s[0:1]
	v_add_u32_e32 v161, 0x16000, v161
	v_fmamk_f32 v144, v176, 0x3a800000, v154
	v_mul_f32_e32 v145, 0x4b800000, v144
	v_cmp_gt_f32_e32 vcc, s40, v144
	s_nop 1
	v_cndmask_b32_e32 v144, v144, v145, vcc
	v_rsq_f32_e32 v144, v144
	s_nop 0
	v_mul_f32_e32 v145, 0x45800000, v144
	v_cndmask_b32_e32 v146, v144, v145, vcc
	v_pk_mul_f32 v[24:25], v[24:25], v[146:147] op_sel_hi:[1,0]
	v_pk_mul_f32 v[26:27], v[26:27], v[146:147] op_sel_hi:[1,0]
	v_pk_mul_f32 v[16:17], v[16:17], v[146:147] op_sel_hi:[1,0]
	v_pk_mul_f32 v[18:19], v[18:19], v[146:147] op_sel_hi:[1,0]
	v_pk_mul_f32 v[28:29], v[28:29], v[146:147] op_sel_hi:[1,0]
	v_pk_mul_f32 v[30:31], v[30:31], v[146:147] op_sel_hi:[1,0]
	v_pk_mul_f32 v[20:21], v[20:21], v[146:147] op_sel_hi:[1,0]
	v_pk_mul_f32 v[22:23], v[22:23], v[146:147] op_sel_hi:[1,0]
	v_pk_mul_f32 v[162:163], v[24:25], v[158:159] op_sel_hi:[1,0]
	v_pk_mul_f32 v[164:165], v[26:27], v[158:159] op_sel_hi:[1,0]
	v_pk_mul_f32 v[166:167], v[16:17], v[158:159] op_sel_hi:[1,0]
	v_pk_mul_f32 v[168:169], v[18:19], v[158:159] op_sel_hi:[1,0]
	v_exp_f32_e32 v162, v162
	v_exp_f32_e32 v163, v163
	v_exp_f32_e32 v164, v164
	v_exp_f32_e32 v165, v165
	v_exp_f32_e32 v166, v166
	v_exp_f32_e32 v167, v167
	v_exp_f32_e32 v168, v168
	v_exp_f32_e32 v169, v169
	v_pk_add_f32 v[162:163], v[162:163], v[160:161] op_sel_hi:[1,0]
	v_pk_add_f32 v[164:165], v[164:165], v[160:161] op_sel_hi:[1,0]
	v_pk_add_f32 v[166:167], v[166:167], v[160:161] op_sel_hi:[1,0]
	v_pk_add_f32 v[168:169], v[168:169], v[160:161] op_sel_hi:[1,0]
	v_rcp_f32_e32 v162, v162
	v_rcp_f32_e32 v163, v163
	v_rcp_f32_e32 v164, v164
	v_rcp_f32_e32 v165, v165
	v_rcp_f32_e32 v166, v166
	v_rcp_f32_e32 v167, v167
	v_rcp_f32_e32 v168, v168
	v_rcp_f32_e32 v169, v169
	v_pk_mul_f32 v[162:163], v[24:25], v[162:163]
	v_pk_mul_f32 v[164:165], v[26:27], v[164:165]
	v_pk_mul_f32 v[166:167], v[16:17], v[166:167]
	v_pk_mul_f32 v[168:169], v[18:19], v[168:169]
	v_pk_mul_f32 v[162:163], v[28:29], v[162:163]
	v_pk_mul_f32 v[164:165], v[30:31], v[164:165]
	v_pk_mul_f32 v[166:167], v[20:21], v[166:167]
	v_pk_mul_f32 v[168:169], v[22:23], v[168:169]
	v_cvt_pk_bf16_f32 v16, v162, v163
	v_cvt_pk_bf16_f32 v17, v164, v165
	v_cvt_pk_bf16_f32 v18, v166, v167
	v_cvt_pk_bf16_f32 v19, v168, v169
	global_store_dwordx4 v161, v[16:19], s[0:1]
	v_add_u32_e32 v161, 0x16000, v161
	v_fmamk_f32 v144, v177, 0x3a800000, v154
	v_mul_f32_e32 v145, 0x4b800000, v144
	v_cmp_gt_f32_e32 vcc, s40, v144
	s_nop 1
	v_cndmask_b32_e32 v144, v144, v145, vcc
	v_rsq_f32_e32 v144, v144
	s_nop 0
	v_mul_f32_e32 v145, 0x45800000, v144
	v_cndmask_b32_e32 v146, v144, v145, vcc
	v_pk_mul_f32 v[8:9], v[8:9], v[146:147] op_sel_hi:[1,0]
	v_pk_mul_f32 v[10:11], v[10:11], v[146:147] op_sel_hi:[1,0]
	v_pk_mul_f32 v[0:1], v[0:1], v[146:147] op_sel_hi:[1,0]
	v_pk_mul_f32 v[2:3], v[2:3], v[146:147] op_sel_hi:[1,0]
	v_pk_mul_f32 v[12:13], v[12:13], v[146:147] op_sel_hi:[1,0]
	v_pk_mul_f32 v[14:15], v[14:15], v[146:147] op_sel_hi:[1,0]
	v_pk_mul_f32 v[4:5], v[4:5], v[146:147] op_sel_hi:[1,0]
	v_pk_mul_f32 v[6:7], v[6:7], v[146:147] op_sel_hi:[1,0]
	v_pk_mul_f32 v[162:163], v[8:9], v[158:159] op_sel_hi:[1,0]
	v_pk_mul_f32 v[164:165], v[10:11], v[158:159] op_sel_hi:[1,0]
	v_pk_mul_f32 v[166:167], v[0:1], v[158:159] op_sel_hi:[1,0]
	v_pk_mul_f32 v[168:169], v[2:3], v[158:159] op_sel_hi:[1,0]
	v_exp_f32_e32 v162, v162
	v_exp_f32_e32 v163, v163
	v_exp_f32_e32 v164, v164
	v_exp_f32_e32 v165, v165
	v_exp_f32_e32 v166, v166
	v_exp_f32_e32 v167, v167
	v_exp_f32_e32 v168, v168
	v_exp_f32_e32 v169, v169
	v_pk_add_f32 v[162:163], v[162:163], v[160:161] op_sel_hi:[1,0]
	v_pk_add_f32 v[164:165], v[164:165], v[160:161] op_sel_hi:[1,0]
	v_pk_add_f32 v[166:167], v[166:167], v[160:161] op_sel_hi:[1,0]
	v_pk_add_f32 v[168:169], v[168:169], v[160:161] op_sel_hi:[1,0]
	v_rcp_f32_e32 v162, v162
	v_rcp_f32_e32 v163, v163
	v_rcp_f32_e32 v164, v164
	v_rcp_f32_e32 v165, v165
	v_rcp_f32_e32 v166, v166
	v_rcp_f32_e32 v167, v167
	v_rcp_f32_e32 v168, v168
	v_rcp_f32_e32 v169, v169
	v_pk_mul_f32 v[162:163], v[8:9], v[162:163]
	v_pk_mul_f32 v[164:165], v[10:11], v[164:165]
	v_pk_mul_f32 v[166:167], v[0:1], v[166:167]
	v_pk_mul_f32 v[168:169], v[2:3], v[168:169]
	v_pk_mul_f32 v[162:163], v[12:13], v[162:163]
	v_pk_mul_f32 v[164:165], v[14:15], v[164:165]
	v_pk_mul_f32 v[166:167], v[4:5], v[166:167]
	v_pk_mul_f32 v[168:169], v[6:7], v[168:169]
	v_cvt_pk_bf16_f32 v0, v162, v163
	v_cvt_pk_bf16_f32 v1, v164, v165
	v_cvt_pk_bf16_f32 v2, v166, v167
	v_cvt_pk_bf16_f32 v3, v168, v169
	global_store_dwordx4 v161, v[0:3], s[0:1]
	s_andn2_b64 vcc, exec, s[4:5]
	s_mov_b64 s[0:1], -1
	s_cbranch_vccnz .LBB0_999
	s_andn2_b64 vcc, exec, s[6:7]
	s_cbranch_vccnz .LBB0_998
	s_barrier
	s_branch .LBB0_998
